# k31: k27 + same second-half residual touch in the final phase (dword loads) + one phase's two serialized residual loads issued together
# speedup vs baseline: 1.0006x; 1.0006x over previous
.LBB0_2293:
	v_lshl_add_u32 v146, s39, 8, v150
	v_lshl_or_b32 v188, s40, 8, v152
	v_ashrrev_i32_e32 v189, 31, v188
	v_ashrrev_i32_e32 v147, 31, v146
	v_lshl_add_u64 v[144:145], v[188:189], 1, s[78:79]
	v_lshlrev_b64 v[148:149], 11, v[146:147]
	v_lshl_add_u64 v[148:149], v[144:145], 0, v[148:149]
	v_or_b32_e32 v190, 16, v146
	global_load_dwordx4 v[156:159], v[148:149], off
	global_load_dwordx4 v[160:163], v[148:149], off offset:256
	v_ashrrev_i32_e32 v191, 31, v190
	v_lshlrev_b64 v[148:149], 11, v[190:191]
	v_or_b32_e32 v192, 32, v146
	v_lshl_add_u64 v[148:149], v[144:145], 0, v[148:149]
	v_ashrrev_i32_e32 v193, 31, v192
	global_load_dwordx4 v[164:167], v[148:149], off
	global_load_dwordx4 v[168:171], v[148:149], off offset:256
	v_lshlrev_b64 v[148:149], 11, v[192:193]
	v_lshl_add_u64 v[148:149], v[144:145], 0, v[148:149]
	global_load_dwordx4 v[172:175], v[148:149], off
	global_load_dwordx4 v[176:179], v[148:149], off offset:256
	v_or_b32_e32 v148, 48, v146
	v_ashrrev_i32_e32 v149, 31, v148
	v_lshlrev_b64 v[180:181], 11, v[148:149]
	v_lshl_add_u64 v[184:185], v[144:145], 0, v[180:181]
	global_load_dwordx4 v[180:183], v[184:185], off
	s_nop 0
	global_load_dwordx4 v[184:187], v[184:185], off offset:256
	v_add_u32_e32 v230, 0x80, v146
	v_mov_b32_e32 v231, 0
	v_lshlrev_b64 v[230:231], 11, v[230:231]
	v_lshl_add_u64 v[230:231], v[144:145], 0, v[230:231]
	v_mov_b32_e32 v242, 0x8000
	v_mov_b32_e32 v243, 0
	global_load_dword v246, v[230:231], off
	global_load_dword v246, v[230:231], off offset:256
	v_lshl_add_u64 v[230:231], v[230:231], 0, v[242:243]
	global_load_dword v246, v[230:231], off
	global_load_dword v246, v[230:231], off offset:256
	v_lshl_add_u64 v[230:231], v[230:231], 0, v[242:243]
	global_load_dword v246, v[230:231], off
	global_load_dword v246, v[230:231], off offset:256
	v_lshl_add_u64 v[230:231], v[230:231], 0, v[242:243]
	global_load_dword v246, v[230:231], off
	global_load_dword v246, v[230:231], off offset:256
	v_readlane_b32 s16, v254, 0
	v_readlane_b32 s18, v254, 2
	v_readlane_b32 s19, v254, 3
	s_mov_b64 s[2:3], s[18:19]
	s_and_b64 vcc, exec, s[6:7]
	v_readlane_b32 s17, v254, 1
	s_waitcnt vmcnt(8) lgkmcnt(15)
	v_lshlrev_b32_e32 v194, 16, v156
	v_and_b32_e32 v195, 0xffff0000, v156
	v_lshlrev_b32_e32 v156, 16, v157
	v_and_b32_e32 v157, 0xffff0000, v157
	v_lshlrev_b32_e32 v196, 16, v158
	v_and_b32_e32 v197, 0xffff0000, v158
	v_lshlrev_b32_e32 v158, 16, v159
	v_and_b32_e32 v159, 0xffff0000, v159
	v_pk_add_f32 v[126:127], v[126:127], v[156:157]
	v_pk_add_f32 v[156:157], v[120:121], v[196:197]
	v_lshlrev_b64 v[120:121], 12, v[146:147]
	v_lshlrev_b32_e32 v198, 16, v160
	v_and_b32_e32 v199, 0xffff0000, v160
	v_lshlrev_b32_e32 v160, 16, v161
	v_and_b32_e32 v161, 0xffff0000, v161
	v_lshlrev_b32_e32 v200, 16, v162
	v_and_b32_e32 v201, 0xffff0000, v162
	v_pk_add_f32 v[158:159], v[122:123], v[158:159]
	v_lshl_add_u64 v[122:123], s[2:3], 0, v[120:121]
	v_lshlrev_b64 v[120:121], 2, v[188:189]
	v_lshlrev_b32_e32 v162, 16, v163
	v_and_b32_e32 v163, 0xffff0000, v163
	v_lshlrev_b32_e32 v202, 16, v164
	v_and_b32_e32 v203, 0xffff0000, v164
	v_pk_add_f32 v[124:125], v[124:125], v[194:195]
	v_lshl_add_u64 v[122:123], v[122:123], 0, v[120:121]
	v_pk_add_f32 v[118:119], v[118:119], v[160:161]
	v_pk_add_f32 v[116:117], v[116:117], v[198:199]
	v_pk_add_f32 v[108:109], v[108:109], v[200:201]
	global_store_dwordx4 v[122:123], v[124:127], off
	global_store_dwordx4 v[122:123], v[156:159], off offset:16
	v_pk_add_f32 v[110:111], v[110:111], v[162:163]
	global_store_dwordx4 v[122:123], v[116:119], off offset:512
	global_store_dwordx4 v[122:123], v[108:111], off offset:528
	v_lshlrev_b32_e32 v164, 16, v165
	v_and_b32_e32 v165, 0xffff0000, v165
	v_pk_add_f32 v[108:109], v[112:113], v[202:203]
	v_lshlrev_b64 v[112:113], 12, v[190:191]
	v_lshlrev_b32_e32 v206, 16, v168
	v_and_b32_e32 v207, 0xffff0000, v168
	v_lshlrev_b32_e32 v168, 16, v169
	v_and_b32_e32 v169, 0xffff0000, v169
	v_lshlrev_b32_e32 v208, 16, v170
	v_and_b32_e32 v209, 0xffff0000, v170
	v_lshl_add_u64 v[112:113], s[2:3], 0, v[112:113]
	v_lshlrev_b32_e32 v204, 16, v166
	v_and_b32_e32 v205, 0xffff0000, v166
	v_lshlrev_b32_e32 v166, 16, v167
	v_and_b32_e32 v167, 0xffff0000, v167
	v_lshlrev_b32_e32 v170, 16, v171
	v_and_b32_e32 v171, 0xffff0000, v171
	v_lshlrev_b32_e32 v210, 16, v172
	v_and_b32_e32 v211, 0xffff0000, v172
	v_pk_add_f32 v[110:111], v[114:115], v[164:165]
	v_lshl_add_u64 v[112:113], v[112:113], 0, v[120:121]
	v_pk_add_f32 v[102:103], v[102:103], v[168:169]
	v_pk_add_f32 v[100:101], v[100:101], v[206:207]
	v_pk_add_f32 v[92:93], v[92:93], v[208:209]
	v_pk_add_f32 v[106:107], v[106:107], v[166:167]
	v_pk_add_f32 v[104:105], v[104:105], v[204:205]
	global_store_dwordx4 v[112:113], v[108:111], off
	global_store_dwordx4 v[112:113], v[104:107], off offset:16
	v_pk_add_f32 v[94:95], v[94:95], v[170:171]
	global_store_dwordx4 v[112:113], v[100:103], off offset:512
	global_store_dwordx4 v[112:113], v[92:95], off offset:528
	v_lshlrev_b32_e32 v172, 16, v173
	v_and_b32_e32 v173, 0xffff0000, v173
	v_pk_add_f32 v[92:93], v[96:97], v[210:211]
	v_lshlrev_b64 v[96:97], 12, v[192:193]
	v_lshlrev_b32_e32 v214, 16, v176
	v_and_b32_e32 v215, 0xffff0000, v176
	v_lshlrev_b32_e32 v176, 16, v177
	v_and_b32_e32 v177, 0xffff0000, v177
	v_lshlrev_b32_e32 v216, 16, v178
	v_and_b32_e32 v217, 0xffff0000, v178
	v_lshl_add_u64 v[96:97], s[2:3], 0, v[96:97]
	v_lshlrev_b32_e32 v212, 16, v174
	v_and_b32_e32 v213, 0xffff0000, v174
	v_lshlrev_b32_e32 v174, 16, v175
	v_and_b32_e32 v175, 0xffff0000, v175
	v_lshlrev_b32_e32 v178, 16, v179
	v_and_b32_e32 v179, 0xffff0000, v179
	v_lshlrev_b32_e32 v218, 16, v180
	v_and_b32_e32 v219, 0xffff0000, v180
	v_pk_add_f32 v[94:95], v[98:99], v[172:173]
	v_lshl_add_u64 v[96:97], v[96:97], 0, v[120:121]
	v_pk_add_f32 v[86:87], v[86:87], v[176:177]
	v_pk_add_f32 v[84:85], v[84:85], v[214:215]
	v_pk_add_f32 v[76:77], v[76:77], v[216:217]
	v_pk_add_f32 v[90:91], v[90:91], v[174:175]
	v_pk_add_f32 v[88:89], v[88:89], v[212:213]
	global_store_dwordx4 v[96:97], v[92:95], off
	global_store_dwordx4 v[96:97], v[88:91], off offset:16
	v_pk_add_f32 v[78:79], v[78:79], v[178:179]
	global_store_dwordx4 v[96:97], v[84:87], off offset:512
	global_store_dwordx4 v[96:97], v[76:79], off offset:528
	v_lshlrev_b32_e32 v180, 16, v181
	v_and_b32_e32 v181, 0xffff0000, v181
	v_pk_add_f32 v[76:77], v[80:81], v[218:219]
	v_lshlrev_b64 v[80:81], 12, v[148:149]
	v_lshlrev_b32_e32 v222, 16, v184
	v_and_b32_e32 v223, 0xffff0000, v184
	v_lshlrev_b32_e32 v184, 16, v185
	v_and_b32_e32 v185, 0xffff0000, v185
	v_lshlrev_b32_e32 v224, 16, v186
	v_and_b32_e32 v225, 0xffff0000, v186
	v_lshl_add_u64 v[80:81], s[2:3], 0, v[80:81]
	v_add_u32_e32 v98, 0x80, v146
	v_lshlrev_b32_e32 v220, 16, v182
	v_and_b32_e32 v221, 0xffff0000, v182
	v_lshlrev_b32_e32 v182, 16, v183
	v_and_b32_e32 v183, 0xffff0000, v183
	v_lshlrev_b32_e32 v186, 16, v187
	v_and_b32_e32 v187, 0xffff0000, v187
	v_pk_add_f32 v[78:79], v[82:83], v[180:181]
	v_lshl_add_u64 v[80:81], v[80:81], 0, v[120:121]
	v_pk_add_f32 v[70:71], v[70:71], v[184:185]
	v_pk_add_f32 v[68:69], v[68:69], v[222:223]
	v_pk_add_f32 v[64:65], v[64:65], v[224:225]
	v_ashrrev_i32_e32 v99, 31, v98
	v_pk_add_f32 v[74:75], v[74:75], v[182:183]
	v_pk_add_f32 v[72:73], v[72:73], v[220:221]
	global_store_dwordx4 v[80:81], v[76:79], off
	global_store_dwordx4 v[80:81], v[72:75], off offset:16
	v_pk_add_f32 v[66:67], v[66:67], v[186:187]
	global_store_dwordx4 v[80:81], v[68:71], off offset:512
	global_store_dwordx4 v[80:81], v[64:67], off offset:528
	v_add_u32_e32 v100, 0x90, v146
	v_ashrrev_i32_e32 v101, 31, v100
	v_lshlrev_b64 v[64:65], 11, v[98:99]
	v_lshl_add_u64 v[64:65], v[144:145], 0, v[64:65]
	global_load_dwordx4 v[66:69], v[64:65], off
	global_load_dwordx4 v[70:73], v[64:65], off offset:256
	v_lshlrev_b64 v[64:65], 11, v[100:101]
	v_add_u32_e32 v102, 0xa0, v146
	v_lshl_add_u64 v[64:65], v[144:145], 0, v[64:65]
	v_ashrrev_i32_e32 v103, 31, v102
	global_load_dwordx4 v[74:77], v[64:65], off
	global_load_dwordx4 v[78:81], v[64:65], off offset:256
	v_lshlrev_b64 v[64:65], 11, v[102:103]
	v_lshl_add_u64 v[64:65], v[144:145], 0, v[64:65]
	global_load_dwordx4 v[82:85], v[64:65], off
	global_load_dwordx4 v[86:89], v[64:65], off offset:256
	v_add_u32_e32 v64, 0xb0, v146
	v_ashrrev_i32_e32 v65, 31, v64
	v_lshlrev_b64 v[90:91], 11, v[64:65]
	v_lshl_add_u64 v[94:95], v[144:145], 0, v[90:91]
	global_load_dwordx4 v[90:93], v[94:95], off
	s_nop 0
	global_load_dwordx4 v[94:97], v[94:95], off offset:256
	s_waitcnt vmcnt(7)
	v_lshlrev_b32_e32 v104, 16, v66
	v_and_b32_e32 v105, 0xffff0000, v66
	v_lshlrev_b32_e32 v66, 16, v67
	v_and_b32_e32 v67, 0xffff0000, v67
	v_pk_add_f32 v[62:63], v[62:63], v[66:67]
	v_lshlrev_b64 v[66:67], 12, v[98:99]
	s_waitcnt vmcnt(6)
	v_lshlrev_b32_e32 v108, 16, v70
	v_and_b32_e32 v109, 0xffff0000, v70
	v_lshlrev_b32_e32 v70, 16, v71
	v_and_b32_e32 v71, 0xffff0000, v71
	v_lshlrev_b32_e32 v110, 16, v72
	v_and_b32_e32 v111, 0xffff0000, v72
	v_lshl_add_u64 v[66:67], s[2:3], 0, v[66:67]
	v_lshlrev_b32_e32 v106, 16, v68
	v_and_b32_e32 v107, 0xffff0000, v68
	v_lshlrev_b32_e32 v68, 16, v69
	v_and_b32_e32 v69, 0xffff0000, v69
	v_lshlrev_b32_e32 v72, 16, v73
	v_and_b32_e32 v73, 0xffff0000, v73
	s_waitcnt vmcnt(5)
	v_lshlrev_b32_e32 v112, 16, v74
	v_and_b32_e32 v113, 0xffff0000, v74
	v_pk_add_f32 v[60:61], v[60:61], v[104:105]
	v_lshl_add_u64 v[66:67], v[66:67], 0, v[120:121]
	v_pk_add_f32 v[54:55], v[54:55], v[70:71]
	v_pk_add_f32 v[52:53], v[52:53], v[108:109]
	v_pk_add_f32 v[44:45], v[44:45], v[110:111]
	v_pk_add_f32 v[58:59], v[58:59], v[68:69]
	v_pk_add_f32 v[56:57], v[56:57], v[106:107]
	global_store_dwordx4 v[66:67], v[60:63], off
	global_store_dwordx4 v[66:67], v[56:59], off offset:16
	v_pk_add_f32 v[46:47], v[46:47], v[72:73]
	global_store_dwordx4 v[66:67], v[52:55], off offset:512
	global_store_dwordx4 v[66:67], v[44:47], off offset:528
	v_lshlrev_b32_e32 v74, 16, v75
	v_and_b32_e32 v75, 0xffff0000, v75
	v_pk_add_f32 v[44:45], v[48:49], v[112:113]
	v_lshlrev_b64 v[48:49], 12, v[100:101]
	s_waitcnt vmcnt(8)
	v_lshlrev_b32_e32 v116, 16, v78
	v_and_b32_e32 v117, 0xffff0000, v78
	v_lshlrev_b32_e32 v78, 16, v79
	v_and_b32_e32 v79, 0xffff0000, v79
	v_lshlrev_b32_e32 v118, 16, v80
	v_and_b32_e32 v119, 0xffff0000, v80
	v_lshl_add_u64 v[48:49], s[2:3], 0, v[48:49]
	v_lshlrev_b32_e32 v114, 16, v76
	v_and_b32_e32 v115, 0xffff0000, v76
	v_lshlrev_b32_e32 v76, 16, v77
	v_and_b32_e32 v77, 0xffff0000, v77
	v_lshlrev_b32_e32 v80, 16, v81
	v_and_b32_e32 v81, 0xffff0000, v81
	s_waitcnt vmcnt(7)
	v_lshlrev_b32_e32 v122, 16, v82
	v_and_b32_e32 v123, 0xffff0000, v82
	v_pk_add_f32 v[46:47], v[50:51], v[74:75]
	v_lshl_add_u64 v[48:49], v[48:49], 0, v[120:121]
	v_pk_add_f32 v[38:39], v[38:39], v[78:79]
	v_pk_add_f32 v[36:37], v[36:37], v[116:117]
	v_pk_add_f32 v[28:29], v[28:29], v[118:119]
	v_pk_add_f32 v[42:43], v[42:43], v[76:77]
	v_pk_add_f32 v[40:41], v[40:41], v[114:115]
	global_store_dwordx4 v[48:49], v[44:47], off
	global_store_dwordx4 v[48:49], v[40:43], off offset:16
	v_pk_add_f32 v[30:31], v[30:31], v[80:81]
	global_store_dwordx4 v[48:49], v[36:39], off offset:512
	global_store_dwordx4 v[48:49], v[28:31], off offset:528
	v_lshlrev_b32_e32 v82, 16, v83
	v_and_b32_e32 v83, 0xffff0000, v83
	v_pk_add_f32 v[28:29], v[32:33], v[122:123]
	v_lshlrev_b64 v[32:33], 12, v[102:103]
	s_waitcnt vmcnt(10)
	v_lshlrev_b32_e32 v126, 16, v86
	v_and_b32_e32 v127, 0xffff0000, v86
	v_lshlrev_b32_e32 v86, 16, v87
	v_and_b32_e32 v87, 0xffff0000, v87
	v_lshlrev_b32_e32 v144, 16, v88
	v_and_b32_e32 v145, 0xffff0000, v88
	v_lshl_add_u64 v[32:33], s[2:3], 0, v[32:33]
	v_lshlrev_b32_e32 v124, 16, v84
	v_and_b32_e32 v125, 0xffff0000, v84
	v_lshlrev_b32_e32 v84, 16, v85
	v_and_b32_e32 v85, 0xffff0000, v85
	v_lshlrev_b32_e32 v88, 16, v89
	v_and_b32_e32 v89, 0xffff0000, v89
	s_waitcnt vmcnt(9)
	v_lshlrev_b32_e32 v146, 16, v90
	v_and_b32_e32 v147, 0xffff0000, v90
	v_pk_add_f32 v[30:31], v[34:35], v[82:83]
	v_lshl_add_u64 v[32:33], v[32:33], 0, v[120:121]
	v_pk_add_f32 v[22:23], v[22:23], v[86:87]
	v_pk_add_f32 v[20:21], v[20:21], v[126:127]
	v_pk_add_f32 v[12:13], v[12:13], v[144:145]
	v_pk_add_f32 v[26:27], v[26:27], v[84:85]
	v_pk_add_f32 v[24:25], v[24:25], v[124:125]
	global_store_dwordx4 v[32:33], v[28:31], off
	global_store_dwordx4 v[32:33], v[24:27], off offset:16
	v_pk_add_f32 v[14:15], v[14:15], v[88:89]
	global_store_dwordx4 v[32:33], v[20:23], off offset:512
	global_store_dwordx4 v[32:33], v[12:15], off offset:528
	v_lshlrev_b32_e32 v90, 16, v91
	v_and_b32_e32 v91, 0xffff0000, v91
	v_pk_add_f32 v[12:13], v[16:17], v[146:147]
	v_lshlrev_b64 v[16:17], 12, v[64:65]
	s_waitcnt vmcnt(12)
	v_lshlrev_b32_e32 v156, 16, v94
	v_and_b32_e32 v157, 0xffff0000, v94
	v_lshlrev_b32_e32 v94, 16, v95
	v_and_b32_e32 v95, 0xffff0000, v95
	v_lshl_add_u64 v[16:17], s[2:3], 0, v[16:17]
	v_lshlrev_b32_e32 v148, 16, v92
	v_and_b32_e32 v149, 0xffff0000, v92
	v_lshlrev_b32_e32 v92, 16, v93
	v_and_b32_e32 v93, 0xffff0000, v93
	v_lshlrev_b32_e32 v158, 16, v96
	v_and_b32_e32 v159, 0xffff0000, v96
	v_lshlrev_b32_e32 v96, 16, v97
	v_and_b32_e32 v97, 0xffff0000, v97
	v_pk_add_f32 v[14:15], v[18:19], v[90:91]
	v_lshl_add_u64 v[16:17], v[16:17], 0, v[120:121]
	v_pk_add_f32 v[6:7], v[6:7], v[94:95]
	v_pk_add_f32 v[4:5], v[4:5], v[156:157]
	v_pk_add_f32 v[10:11], v[10:11], v[92:93]
	v_pk_add_f32 v[8:9], v[8:9], v[148:149]
	global_store_dwordx4 v[16:17], v[12:15], off
	global_store_dwordx4 v[16:17], v[8:11], off offset:16
	v_pk_add_f32 v[2:3], v[2:3], v[96:97]
	v_pk_add_f32 v[0:1], v[0:1], v[158:159]
	global_store_dwordx4 v[16:17], v[4:7], off offset:512
	global_store_dwordx4 v[16:17], v[0:3], off offset:528
	s_mov_b64 s[2:3], -1
	s_cbranch_vccnz .LBB0_2278
	s_andn2_b64 vcc, exec, s[8:9]
	s_cbranch_vccnz .LBB0_2277
	s_barrier
	s_branch .LBB0_2277
